# SGPR-base LDS-DMA form in all five GEMM K-loops (WOUT and DOWN added)
# baseline (speedup 1.0000x reference)
; #define PG8_STAGE(bufoff, gbase, voff) do { _Pragma("unroll") for (int _i = 0; _i < 2; ++_i) \
;         __builtin_amdgcn_global_load_lds((const unsigned*)((const char*)(gbase) + (voff)[_i]), (PG8_LAS unsigned*)(lds + (bufoff) + ldsw + _i * 8192), 16, 0, 0); } while (0)
; #define PG8_LDA(dst, b, h) do { _Pragma("unroll") for (int m = 0; m < 4; ++m) _Pragma("unroll") for (int k = 0; k < 2; ++k) dst[m][k] = *(const PG8_LAS bf16x8*)(lds + PG8_SA(b, h) + aoff + m * 2048 + k * 1024); } while (0)
; #define PG8_LDB(dst, b, h) do { _Pragma("unroll") for (int n = 0; n < 2; ++n) _Pragma("unroll") for (int k = 0; k < 2; ++k) dst[n][k] = *(const PG8_LAS bf16x8*)(lds + PG8_SB(b, h) + boff + n * 2048 + k * 1024); } while (0)
; template <class Epi, class Sched, bool ALIGN_EPI = false, bool SP2 = false>
; __device__ __forceinline__ void gemm_phase(PG8_LAS unsigned char* lds, const Gemm g, const Sched& S, const Epi& E) {
;     ...
;         for (int t = 0; t < nt; t += 2) {
;             const bool last = (t == nt - 2);
;             const char* a1 = cA + (size_t)(t + 1) * kstep;
;             const char* a2 = last ? nA : cA + (size_t)(t + 2) * kstep; const char* b2 = last ? nB : cB + (size_t)(t + 2) * kstep;
;             const char* a3 = a2 + kstep; const char* b3 = b2 + kstep;
;             if (last && has_next) S.a_ready(nxt);
;             if constexpr (SP2) {
;             PG8_LDB(B0, 0, 0); PG8_LDB(B1, 0, 1); PG8_SCHED; PG8_LDA(At, 0, 0); PG8_STAGE(PG8_SA(1, 1), a1 + hstep, voffA);
;             PG8_WAIT_V(8); PG8_WAIT_L(0); PG8_BAR; PG8_MMA(0, 0, At, B0); PG8_MMA(0, 1, At, B1); PG8_BAR; PG8_SCHED;
;             PG8_LDA(At, 0, 1); PG8_STAGE(PG8_SB(0, 0), b2, voffB); PG8_STAGE(PG8_SB(0, 1), b2 + hstep, voffB); PG8_STAGE(PG8_SA(0, 0), a2, voffA);
;             PG8_WAIT_V(8); PG8_WAIT_L(0); PG8_BAR; PG8_MMA(1, 0, At, B0); PG8_MMA(1, 1, At, B1); PG8_BAR; PG8_SCHED;
;             PG8_LDB(B0, 1, 0); PG8_LDB(B1, 1, 1); PG8_SCHED; PG8_LDA(At, 1, 0); PG8_STAGE(PG8_SA(0, 1), a2 + hstep, voffA);
;             PG8_WAIT_V(8); PG8_WAIT_L(0); PG8_BAR; PG8_MMA(0, 0, At, B0); PG8_MMA(0, 1, At, B1); PG8_BAR; PG8_SCHED;
;             PG8_LDA(At, 1, 1); PG8_STAGE(PG8_SB(1, 0), b3, voffB); PG8_STAGE(PG8_SB(1, 1), b3 + hstep, voffB); PG8_STAGE(PG8_SA(1, 0), a3, voffA);
;             PG8_WAIT_V(8); PG8_WAIT_L(0); PG8_BAR; PG8_MMA(1, 0, At, B0); PG8_MMA(1, 1, At, B1); PG8_BAR; PG8_SCHED;
.LBB0_1255:
	s_sub_i32 vcc_hi, 0x29000, s100
	s_sub_i32 vcc_hi, vcc_hi, s101
	s_add_u32 s38, s26, 0x100
	s_addc_u32 s39, s27, 0
	s_add_i32 s64, 0, 0x10000
	s_cmp_eq_u32 s63, 28
	s_cselect_b32 s43, s15, s39
	s_cselect_b32 s42, s59, s38
	s_cselect_b32 s41, s11, s62
	s_cselect_b32 s40, s60, s61
	s_add_i32 s65, 0, 0x14000
	v_add_u32_e32 v148, s64, v171
	v_add_u32_e32 v164, s65, v171
	ds_read_b128 v[136:139], v148
	ds_read_b128 v[140:143], v148 offset:1024
	ds_read_b128 v[144:147], v148 offset:2048
	ds_read_b128 v[148:151], v148 offset:3072
	ds_read_b128 v[152:155], v164
	ds_read_b128 v[156:159], v164 offset:1024
	ds_read_b128 v[160:163], v164 offset:2048
	ds_read_b128 v[164:167], v164 offset:3072
	s_add_i32 m0, s23, 0xc000
	v_add_u32_e32 v250, s100, v173
	ds_read_b128 v[174:177], v250
	ds_read_b128 v[178:181], v250 offset:1024
	ds_read_b128 v[182:185], v250 offset:2048
	ds_read_b128 v[186:189], v250 offset:3072
	ds_read_b128 v[190:193], v250 offset:4096
	ds_read_b128 v[202:205], v250 offset:5120
	ds_read_b128 v[206:209], v250 offset:6144
	ds_read_b128 v[210:213], v250 offset:7168
	global_load_lds_dwordx4 v132, s[26:27]
	s_add_i32 m0, s23, 0xe000
	s_nop 0
	global_load_lds_dwordx4 v134, s[26:27]
	s_add_i32 m0, vcc_hi, s23
	s_nop 0
	global_load_lds_dwordx4 v0, s[42:43]
	s_add_i32 m0, m0, 0x2000
	s_nop 0
	global_load_lds_dwordx4 v130, s[42:43]
	s_waitcnt vmcnt(10)
	s_waitcnt lgkmcnt(0)
	s_setprio 1
	s_waitcnt lgkmcnt(0)
	v_mfma_f32_16x16x32_bf16 v[98:101], v[136:139], v[174:177], v[98:101]
	v_mfma_f32_16x16x32_bf16 v[78:81], v[144:147], v[174:177], v[78:81]
	v_mfma_f32_16x16x32_bf16 v[102:105], v[136:139], v[182:185], v[102:105]
	v_mfma_f32_16x16x32_bf16 v[74:77], v[144:147], v[182:185], v[74:77]
	s_barrier
	v_mfma_f32_16x16x32_bf16 v[106:109], v[136:139], v[190:193], v[106:109]
	v_mfma_f32_16x16x32_bf16 v[70:73], v[144:147], v[190:193], v[70:73]
	v_mfma_f32_16x16x32_bf16 v[110:113], v[136:139], v[206:209], v[110:113]
	v_mfma_f32_16x16x32_bf16 v[66:69], v[144:147], v[206:209], v[66:69]
	v_mfma_f32_16x16x32_bf16 v[98:101], v[140:143], v[178:181], v[98:101]
	v_mfma_f32_16x16x32_bf16 v[78:81], v[148:151], v[178:181], v[78:81]
	v_mfma_f32_16x16x32_bf16 v[102:105], v[140:143], v[186:189], v[102:105]
	v_mfma_f32_16x16x32_bf16 v[74:77], v[148:151], v[186:189], v[74:77]
	v_mfma_f32_16x16x32_bf16 v[106:109], v[140:143], v[202:205], v[106:109]
	v_mfma_f32_16x16x32_bf16 v[70:73], v[148:151], v[202:205], v[70:73]
	v_mfma_f32_16x16x32_bf16 v[110:113], v[140:143], v[210:213], v[110:113]
	v_mfma_f32_16x16x32_bf16 v[66:69], v[148:151], v[210:213], v[66:69]
	s_setprio 0
	s_setprio 1
	v_mfma_f32_16x16x32_bf16 v[46:49], v[152:155], v[174:177], v[46:49]
	v_mfma_f32_16x16x32_bf16 v[2:5], v[160:163], v[174:177], v[2:5]
	v_mfma_f32_16x16x32_bf16 v[42:45], v[152:155], v[182:185], v[42:45]
	v_mfma_f32_16x16x32_bf16 v[6:9], v[160:163], v[182:185], v[6:9]
	v_mfma_f32_16x16x32_bf16 v[38:41], v[152:155], v[190:193], v[38:41]
	v_mfma_f32_16x16x32_bf16 v[10:13], v[160:163], v[190:193], v[10:13]
	v_mfma_f32_16x16x32_bf16 v[34:37], v[152:155], v[206:209], v[34:37]
	v_mfma_f32_16x16x32_bf16 v[14:17], v[160:163], v[206:209], v[14:17]
	v_mfma_f32_16x16x32_bf16 v[46:49], v[156:159], v[178:181], v[46:49]
	v_mfma_f32_16x16x32_bf16 v[2:5], v[164:167], v[178:181], v[2:5]
	v_mfma_f32_16x16x32_bf16 v[42:45], v[156:159], v[186:189], v[42:45]
	v_mfma_f32_16x16x32_bf16 v[6:9], v[164:167], v[186:189], v[6:9]
	v_mfma_f32_16x16x32_bf16 v[38:41], v[156:159], v[202:205], v[38:41]
	v_mfma_f32_16x16x32_bf16 v[10:13], v[164:167], v[202:205], v[10:13]
	v_mfma_f32_16x16x32_bf16 v[34:37], v[156:159], v[210:213], v[34:37]
	v_mfma_f32_16x16x32_bf16 v[14:17], v[164:167], v[210:213], v[14:17]
	s_setprio 0
	s_barrier
	s_add_i32 s26, s64, s44
	s_mov_b32 m0, s26
	ds_read_b128 v[174:177], v173 offset:16384
	ds_read_b128 v[178:181], v173 offset:17408
	ds_read_b128 v[182:185], v173 offset:18432
	ds_read_b128 v[186:189], v173 offset:19456
	ds_read_b128 v[190:193], v173 offset:20480
	ds_read_b128 v[202:205], v173 offset:21504
	ds_read_b128 v[206:209], v173 offset:22528
	ds_read_b128 v[210:213], v173 offset:23552
	global_load_lds_dwordx4 v0, s[40:41]
	s_add_i32 m0, s26, 0x2000
	s_add_u32 s26, s40, 0x80000
	s_addc_u32 s27, s41, 0
	s_add_i32 s64, s65, s44
	global_load_lds_dwordx4 v130, s[40:41]
	s_mov_b32 m0, s64
	s_nop 0
	global_load_lds_dwordx4 v0, s[26:27]
	s_add_i32 m0, s64, 0x2000
	s_nop 0
	global_load_lds_dwordx4 v130, s[26:27]
	s_waitcnt vmcnt(8)
	s_waitcnt lgkmcnt(0)
	s_setprio 1
	s_waitcnt lgkmcnt(0)
	v_mfma_f32_16x16x32_bf16 v[114:117], v[136:139], v[174:177], v[114:117]
	v_mfma_f32_16x16x32_bf16 v[94:97], v[144:147], v[174:177], v[94:97]
	v_mfma_f32_16x16x32_bf16 v[118:121], v[136:139], v[182:185], v[118:121]
	v_mfma_f32_16x16x32_bf16 v[90:93], v[144:147], v[182:185], v[90:93]
	s_barrier
; #define PG8_STAGE(bufoff, gbase, voff) do { _Pragma("unroll") for (int _i = 0; _i < 2; ++_i) \
;         __builtin_amdgcn_global_load_lds((const unsigned*)((const char*)(gbase) + (voff)[_i]), (PG8_LAS unsigned*)(lds + (bufoff) + ldsw + _i * 8192), 16, 0, 0); } while (0)
; #define PG8_LDA(dst, b, h) do { _Pragma("unroll") for (int m = 0; m < 4; ++m) _Pragma("unroll") for (int k = 0; k < 2; ++k) dst[m][k] = *(const PG8_LAS bf16x8*)(lds + PG8_SA(b, h) + aoff + m * 2048 + k * 1024); } while (0)
; #define PG8_LDB(dst, b, h) do { _Pragma("unroll") for (int n = 0; n < 2; ++n) _Pragma("unroll") for (int k = 0; k < 2; ++k) dst[n][k] = *(const PG8_LAS bf16x8*)(lds + PG8_SB(b, h) + boff + n * 2048 + k * 1024); } while (0)
; template <class Epi, class Sched, bool ALIGN_EPI = false, bool SP2 = false>
; __device__ __forceinline__ void gemm_phase(PG8_LAS unsigned char* lds, const Gemm g, const Sched& S, const Epi& E) {
;     ...
;         for (int t = 0; t < nt; t += 2) {
;             const bool last = (t == nt - 2);
;             const char* a1 = cA + (size_t)(t + 1) * kstep;
;             const char* a2 = last ? nA : cA + (size_t)(t + 2) * kstep; const char* b2 = last ? nB : cB + (size_t)(t + 2) * kstep;
;             const char* a3 = a2 + kstep; const char* b3 = b2 + kstep;
;             if (last && has_next) S.a_ready(nxt);
;             if constexpr (SP2) {
;             PG8_LDB(B0, 0, 0); PG8_LDB(B1, 0, 1); PG8_SCHED; PG8_LDA(At, 0, 0); PG8_STAGE(PG8_SA(1, 1), a1 + hstep, voffA);
;             PG8_WAIT_V(8); PG8_WAIT_L(0); PG8_BAR; PG8_MMA(0, 0, At, B0); PG8_MMA(0, 1, At, B1); PG8_BAR; PG8_SCHED;
;             PG8_LDA(At, 0, 1); PG8_STAGE(PG8_SB(0, 0), b2, voffB); PG8_STAGE(PG8_SB(0, 1), b2 + hstep, voffB); PG8_STAGE(PG8_SA(0, 0), a2, voffA);
;             PG8_WAIT_V(8); PG8_WAIT_L(0); PG8_BAR; PG8_MMA(1, 0, At, B0); PG8_MMA(1, 1, At, B1); PG8_BAR; PG8_SCHED;
;             PG8_LDB(B0, 1, 0); PG8_LDB(B1, 1, 1); PG8_SCHED; PG8_LDA(At, 1, 0); PG8_STAGE(PG8_SA(0, 1), a2 + hstep, voffA);
;             PG8_WAIT_V(8); PG8_WAIT_L(0); PG8_BAR; PG8_MMA(0, 0, At, B0); PG8_MMA(0, 1, At, B1); PG8_BAR; PG8_SCHED;
;             PG8_LDA(At, 1, 1); PG8_STAGE(PG8_SB(1, 0), b3, voffB); PG8_STAGE(PG8_SB(1, 1), b3 + hstep, voffB); PG8_STAGE(PG8_SA(1, 0), a3, voffA);
;             PG8_WAIT_V(8); PG8_WAIT_L(0); PG8_BAR; PG8_MMA(1, 0, At, B0); PG8_MMA(1, 1, At, B1); PG8_BAR; PG8_SCHED;
	v_mfma_f32_16x16x32_bf16 v[122:125], v[136:139], v[190:193], v[122:125]
	v_mfma_f32_16x16x32_bf16 v[86:89], v[144:147], v[190:193], v[86:89]
	v_mfma_f32_16x16x32_bf16 v[126:129], v[136:139], v[206:209], v[126:129]
	v_mfma_f32_16x16x32_bf16 v[82:85], v[144:147], v[206:209], v[82:85]
	v_mfma_f32_16x16x32_bf16 v[114:117], v[140:143], v[178:181], v[114:117]
	v_mfma_f32_16x16x32_bf16 v[94:97], v[148:151], v[178:181], v[94:97]
	v_mfma_f32_16x16x32_bf16 v[118:121], v[140:143], v[186:189], v[118:121]
	v_mfma_f32_16x16x32_bf16 v[90:93], v[148:151], v[186:189], v[90:93]
	v_mfma_f32_16x16x32_bf16 v[122:125], v[140:143], v[202:205], v[122:125]
	v_mfma_f32_16x16x32_bf16 v[86:89], v[148:151], v[202:205], v[86:89]
	v_mfma_f32_16x16x32_bf16 v[126:129], v[140:143], v[210:213], v[126:129]
	v_mfma_f32_16x16x32_bf16 v[82:85], v[148:151], v[210:213], v[82:85]
	s_setprio 0
	s_setprio 1
	v_mfma_f32_16x16x32_bf16 v[62:65], v[152:155], v[174:177], v[62:65]
	v_mfma_f32_16x16x32_bf16 v[18:21], v[160:163], v[174:177], v[18:21]
	v_mfma_f32_16x16x32_bf16 v[58:61], v[152:155], v[182:185], v[58:61]
	v_mfma_f32_16x16x32_bf16 v[22:25], v[160:163], v[182:185], v[22:25]
	v_mfma_f32_16x16x32_bf16 v[54:57], v[152:155], v[190:193], v[54:57]
	v_mfma_f32_16x16x32_bf16 v[26:29], v[160:163], v[190:193], v[26:29]
	v_mfma_f32_16x16x32_bf16 v[50:53], v[152:155], v[206:209], v[50:53]
	v_mfma_f32_16x16x32_bf16 v[30:33], v[160:163], v[206:209], v[30:33]
	v_mfma_f32_16x16x32_bf16 v[62:65], v[156:159], v[178:181], v[62:65]
	v_mfma_f32_16x16x32_bf16 v[18:21], v[164:167], v[178:181], v[18:21]
	v_mfma_f32_16x16x32_bf16 v[58:61], v[156:159], v[186:189], v[58:61]
	v_mfma_f32_16x16x32_bf16 v[22:25], v[164:167], v[186:189], v[22:25]
	v_mfma_f32_16x16x32_bf16 v[54:57], v[156:159], v[202:205], v[54:57]
	v_mfma_f32_16x16x32_bf16 v[26:29], v[164:167], v[202:205], v[26:29]
	v_mfma_f32_16x16x32_bf16 v[50:53], v[156:159], v[210:213], v[50:53]
	v_mfma_f32_16x16x32_bf16 v[30:33], v[164:167], v[210:213], v[30:33]
	s_setprio 0
	s_barrier
	s_add_i32 s64, 0, 0x18000
	s_add_i32 s65, 0, 0x1c000
	v_add_u32_e32 v148, s64, v171
	v_add_u32_e32 v164, s65, v171
	ds_read_b128 v[136:139], v148
	ds_read_b128 v[140:143], v148 offset:1024
	ds_read_b128 v[144:147], v148 offset:2048
	ds_read_b128 v[148:151], v148 offset:3072
	ds_read_b128 v[152:155], v164
	ds_read_b128 v[156:159], v164 offset:1024
	ds_read_b128 v[160:163], v164 offset:2048
	ds_read_b128 v[164:167], v164 offset:3072
	s_add_u32 s26, s42, 0x80000
	s_addc_u32 s27, s43, 0
	s_mov_b32 m0, s46
	v_add_u32_e32 v250, s101, v173
	ds_read_b128 v[174:177], v250
	ds_read_b128 v[178:181], v250 offset:1024
	ds_read_b128 v[182:185], v250 offset:2048
	ds_read_b128 v[186:189], v250 offset:3072
	ds_read_b128 v[190:193], v250 offset:4096
	ds_read_b128 v[202:205], v250 offset:5120
	ds_read_b128 v[206:209], v250 offset:6144
	ds_read_b128 v[210:213], v250 offset:7168
	global_load_lds_dwordx4 v0, s[26:27]
	s_mov_b32 m0, s47
	s_nop 0
	global_load_lds_dwordx4 v130, s[26:27]
	s_add_i32 m0, s100, s23
	s_nop 0
	s_add_u32 s42, s42, 0x80
	s_addc_u32 s43, s43, 0
	global_load_lds_dwordx4 v0, s[42:43]
	s_add_i32 m0, m0, 0x2000
	s_nop 0
	global_load_lds_dwordx4 v130, s[42:43]
	s_waitcnt vmcnt(10)
	s_waitcnt lgkmcnt(0)
	s_setprio 1
	s_waitcnt lgkmcnt(0)
	v_mfma_f32_16x16x32_bf16 v[98:101], v[136:139], v[174:177], v[98:101]
	v_mfma_f32_16x16x32_bf16 v[78:81], v[144:147], v[174:177], v[78:81]
	v_mfma_f32_16x16x32_bf16 v[102:105], v[136:139], v[182:185], v[102:105]
	v_mfma_f32_16x16x32_bf16 v[74:77], v[144:147], v[182:185], v[74:77]
	s_barrier
; #define PG8_STAGE(bufoff, gbase, voff) do { _Pragma("unroll") for (int _i = 0; _i < 2; ++_i) \
;         __builtin_amdgcn_global_load_lds((const unsigned*)((const char*)(gbase) + (voff)[_i]), (PG8_LAS unsigned*)(lds + (bufoff) + ldsw + _i * 8192), 16, 0, 0); } while (0)
; #define PG8_LDA(dst, b, h) do { _Pragma("unroll") for (int m = 0; m < 4; ++m) _Pragma("unroll") for (int k = 0; k < 2; ++k) dst[m][k] = *(const PG8_LAS bf16x8*)(lds + PG8_SA(b, h) + aoff + m * 2048 + k * 1024); } while (0)
; #define PG8_LDB(dst, b, h) do { _Pragma("unroll") for (int n = 0; n < 2; ++n) _Pragma("unroll") for (int k = 0; k < 2; ++k) dst[n][k] = *(const PG8_LAS bf16x8*)(lds + PG8_SB(b, h) + boff + n * 2048 + k * 1024); } while (0)
; template <class Epi, class Sched, bool ALIGN_EPI = false, bool SP2 = false>
; __device__ __forceinline__ void gemm_phase(PG8_LAS unsigned char* lds, const Gemm g, const Sched& S, const Epi& E) {
;     ...
;         for (int t = 0; t < nt; t += 2) {
;             const bool last = (t == nt - 2);
;             const char* a1 = cA + (size_t)(t + 1) * kstep;
;             const char* a2 = last ? nA : cA + (size_t)(t + 2) * kstep; const char* b2 = last ? nB : cB + (size_t)(t + 2) * kstep;
;             const char* a3 = a2 + kstep; const char* b3 = b2 + kstep;
;             if (last && has_next) S.a_ready(nxt);
;             if constexpr (SP2) {
;             PG8_LDB(B0, 0, 0); PG8_LDB(B1, 0, 1); PG8_SCHED; PG8_LDA(At, 0, 0); PG8_STAGE(PG8_SA(1, 1), a1 + hstep, voffA);
;             PG8_WAIT_V(8); PG8_WAIT_L(0); PG8_BAR; PG8_MMA(0, 0, At, B0); PG8_MMA(0, 1, At, B1); PG8_BAR; PG8_SCHED;
;             PG8_LDA(At, 0, 1); PG8_STAGE(PG8_SB(0, 0), b2, voffB); PG8_STAGE(PG8_SB(0, 1), b2 + hstep, voffB); PG8_STAGE(PG8_SA(0, 0), a2, voffA);
;             PG8_WAIT_V(8); PG8_WAIT_L(0); PG8_BAR; PG8_MMA(1, 0, At, B0); PG8_MMA(1, 1, At, B1); PG8_BAR; PG8_SCHED;
;             PG8_LDB(B0, 1, 0); PG8_LDB(B1, 1, 1); PG8_SCHED; PG8_LDA(At, 1, 0); PG8_STAGE(PG8_SA(0, 1), a2 + hstep, voffA);
;             PG8_WAIT_V(8); PG8_WAIT_L(0); PG8_BAR; PG8_MMA(0, 0, At, B0); PG8_MMA(0, 1, At, B1); PG8_BAR; PG8_SCHED;
;             PG8_LDA(At, 1, 1); PG8_STAGE(PG8_SB(1, 0), b3, voffB); PG8_STAGE(PG8_SB(1, 1), b3 + hstep, voffB); PG8_STAGE(PG8_SA(1, 0), a3, voffA);
;             PG8_WAIT_V(8); PG8_WAIT_L(0); PG8_BAR; PG8_MMA(1, 0, At, B0); PG8_MMA(1, 1, At, B1); PG8_BAR; PG8_SCHED;
	v_mfma_f32_16x16x32_bf16 v[106:109], v[136:139], v[190:193], v[106:109]
	v_mfma_f32_16x16x32_bf16 v[70:73], v[144:147], v[190:193], v[70:73]
	v_mfma_f32_16x16x32_bf16 v[110:113], v[136:139], v[206:209], v[110:113]
	v_mfma_f32_16x16x32_bf16 v[66:69], v[144:147], v[206:209], v[66:69]
	v_mfma_f32_16x16x32_bf16 v[98:101], v[140:143], v[178:181], v[98:101]
	v_mfma_f32_16x16x32_bf16 v[78:81], v[148:151], v[178:181], v[78:81]
	v_mfma_f32_16x16x32_bf16 v[102:105], v[140:143], v[186:189], v[102:105]
	v_mfma_f32_16x16x32_bf16 v[74:77], v[148:151], v[186:189], v[74:77]
	v_mfma_f32_16x16x32_bf16 v[106:109], v[140:143], v[202:205], v[106:109]
	v_mfma_f32_16x16x32_bf16 v[70:73], v[148:151], v[202:205], v[70:73]
	v_mfma_f32_16x16x32_bf16 v[110:113], v[140:143], v[210:213], v[110:113]
	v_mfma_f32_16x16x32_bf16 v[66:69], v[148:151], v[210:213], v[66:69]
	s_setprio 0
	s_setprio 1
	v_mfma_f32_16x16x32_bf16 v[46:49], v[152:155], v[174:177], v[46:49]
	v_mfma_f32_16x16x32_bf16 v[2:5], v[160:163], v[174:177], v[2:5]
	v_mfma_f32_16x16x32_bf16 v[42:45], v[152:155], v[182:185], v[42:45]
	v_mfma_f32_16x16x32_bf16 v[6:9], v[160:163], v[182:185], v[6:9]
	v_mfma_f32_16x16x32_bf16 v[38:41], v[152:155], v[190:193], v[38:41]
	v_mfma_f32_16x16x32_bf16 v[10:13], v[160:163], v[190:193], v[10:13]
	v_mfma_f32_16x16x32_bf16 v[34:37], v[152:155], v[206:209], v[34:37]
	v_mfma_f32_16x16x32_bf16 v[14:17], v[160:163], v[206:209], v[14:17]
	v_mfma_f32_16x16x32_bf16 v[46:49], v[156:159], v[178:181], v[46:49]
	v_mfma_f32_16x16x32_bf16 v[2:5], v[164:167], v[178:181], v[2:5]
	v_mfma_f32_16x16x32_bf16 v[42:45], v[156:159], v[186:189], v[42:45]
	v_mfma_f32_16x16x32_bf16 v[6:9], v[164:167], v[186:189], v[6:9]
	v_mfma_f32_16x16x32_bf16 v[38:41], v[156:159], v[202:205], v[38:41]
	v_mfma_f32_16x16x32_bf16 v[10:13], v[164:167], v[202:205], v[10:13]
	v_mfma_f32_16x16x32_bf16 v[34:37], v[156:159], v[210:213], v[34:37]
	v_mfma_f32_16x16x32_bf16 v[14:17], v[164:167], v[210:213], v[14:17]
	s_setprio 0
	s_barrier
	s_add_i32 s26, s64, s44
	s_mov_b32 m0, s26
	ds_read_b128 v[174:177], v173 offset:49152
	ds_read_b128 v[178:181], v173 offset:50176
	ds_read_b128 v[182:185], v173 offset:51200
	ds_read_b128 v[186:189], v173 offset:52224
	ds_read_b128 v[190:193], v173 offset:53248
	ds_read_b128 v[202:205], v173 offset:54272
	ds_read_b128 v[206:209], v173 offset:55296
	ds_read_b128 v[210:213], v173 offset:56320
	s_add_u32 s40, s40, 0x80
	s_addc_u32 s41, s41, 0
	global_load_lds_dwordx4 v0, s[40:41]
	s_add_i32 m0, s26, 0x2000
	s_add_u32 s26, s40, 0x80000
	s_addc_u32 s27, s41, 0
	global_load_lds_dwordx4 v130, s[40:41]
	s_add_i32 s40, s65, s44
	s_mov_b32 m0, s40
	s_nop 0
	global_load_lds_dwordx4 v0, s[26:27]
	s_add_i32 m0, s40, 0x2000
	s_nop 0
	global_load_lds_dwordx4 v130, s[26:27]
	s_waitcnt vmcnt(8)
	s_waitcnt lgkmcnt(0)
	s_setprio 1
	s_waitcnt lgkmcnt(0)
	v_mfma_f32_16x16x32_bf16 v[114:117], v[136:139], v[174:177], v[114:117]
	v_mfma_f32_16x16x32_bf16 v[94:97], v[144:147], v[174:177], v[94:97]
	v_mfma_f32_16x16x32_bf16 v[118:121], v[136:139], v[182:185], v[118:121]
	v_mfma_f32_16x16x32_bf16 v[90:93], v[144:147], v[182:185], v[90:93]
	s_barrier
	v_mfma_f32_16x16x32_bf16 v[122:125], v[136:139], v[190:193], v[122:125]
	v_mfma_f32_16x16x32_bf16 v[86:89], v[144:147], v[190:193], v[86:89]
	v_mfma_f32_16x16x32_bf16 v[126:129], v[136:139], v[206:209], v[126:129]
	v_mfma_f32_16x16x32_bf16 v[82:85], v[144:147], v[206:209], v[82:85]
	v_mfma_f32_16x16x32_bf16 v[114:117], v[140:143], v[178:181], v[114:117]
	v_mfma_f32_16x16x32_bf16 v[94:97], v[148:151], v[178:181], v[94:97]
	v_mfma_f32_16x16x32_bf16 v[118:121], v[140:143], v[186:189], v[118:121]
	v_mfma_f32_16x16x32_bf16 v[90:93], v[148:151], v[186:189], v[90:93]
	v_mfma_f32_16x16x32_bf16 v[122:125], v[140:143], v[202:205], v[122:125]
	v_mfma_f32_16x16x32_bf16 v[86:89], v[148:151], v[202:205], v[86:89]
	v_mfma_f32_16x16x32_bf16 v[126:129], v[140:143], v[210:213], v[126:129]
	v_mfma_f32_16x16x32_bf16 v[82:85], v[148:151], v[210:213], v[82:85]
	s_setprio 0
	s_setprio 1
	v_mfma_f32_16x16x32_bf16 v[62:65], v[152:155], v[174:177], v[62:65]
	v_mfma_f32_16x16x32_bf16 v[18:21], v[160:163], v[174:177], v[18:21]
	v_mfma_f32_16x16x32_bf16 v[58:61], v[152:155], v[182:185], v[58:61]
	v_mfma_f32_16x16x32_bf16 v[22:25], v[160:163], v[182:185], v[22:25]
	v_mfma_f32_16x16x32_bf16 v[54:57], v[152:155], v[190:193], v[54:57]
	v_mfma_f32_16x16x32_bf16 v[26:29], v[160:163], v[190:193], v[26:29]
	v_mfma_f32_16x16x32_bf16 v[50:53], v[152:155], v[206:209], v[50:53]
	v_mfma_f32_16x16x32_bf16 v[30:33], v[160:163], v[206:209], v[30:33]
	v_mfma_f32_16x16x32_bf16 v[62:65], v[156:159], v[178:181], v[62:65]
	v_mfma_f32_16x16x32_bf16 v[18:21], v[164:167], v[178:181], v[18:21]
	v_mfma_f32_16x16x32_bf16 v[58:61], v[156:159], v[186:189], v[58:61]
	v_mfma_f32_16x16x32_bf16 v[22:25], v[164:167], v[186:189], v[22:25]
	v_mfma_f32_16x16x32_bf16 v[54:57], v[156:159], v[202:205], v[54:57]
	v_mfma_f32_16x16x32_bf16 v[26:29], v[164:167], v[202:205], v[26:29]
	v_mfma_f32_16x16x32_bf16 v[50:53], v[156:159], v[210:213], v[50:53]
	v_mfma_f32_16x16x32_bf16 v[30:33], v[164:167], v[210:213], v[30:33]
	s_setprio 0
	s_barrier
	s_add_i32 s63, s63, 2
	s_mov_b32 s101, s100
	s_mov_b32 s100, vcc_hi
	s_add_u32 s61, s61, 0x100
	s_addc_u32 s62, s62, 0
	s_cmp_gt_u32 s63, 29
	s_mov_b64 s[26:27], s[38:39]
	s_cbranch_scc0 .LBB0_1255
	s_and_b64 vcc, exec, s[8:9]
	s_cbranch_vccz .LBB0_1258
	s_barrier

; #define PG8_STAGE(bufoff, gbase, voff) do { _Pragma("unroll") for (int _i = 0; _i < 2; ++_i) \
;         __builtin_amdgcn_global_load_lds((const unsigned*)((const char*)(gbase) + (voff)[_i]), (PG8_LAS unsigned*)(lds + (bufoff) + ldsw + _i * 8192), 16, 0, 0); } while (0)
; #define PG8_LDA(dst, b, h) do { _Pragma("unroll") for (int m = 0; m < 4; ++m) _Pragma("unroll") for (int k = 0; k < 2; ++k) dst[m][k] = *(const PG8_LAS bf16x8*)(lds + PG8_SA(b, h) + aoff + m * 2048 + k * 1024); } while (0)
; #define PG8_LDB(dst, b, h) do { _Pragma("unroll") for (int n = 0; n < 2; ++n) _Pragma("unroll") for (int k = 0; k < 2; ++k) dst[n][k] = *(const PG8_LAS bf16x8*)(lds + PG8_SB(b, h) + boff + n * 2048 + k * 1024); } while (0)
; template <class Epi, class Sched, bool ALIGN_EPI = false, bool SP2 = false>
; __device__ __forceinline__ void gemm_phase(PG8_LAS unsigned char* lds, const Gemm g, const Sched& S, const Epi& E) {
;     ...
;         for (int t = 0; t < nt; t += 2) {
;             const bool last = (t == nt - 2);
;             const char* a1 = cA + (size_t)(t + 1) * kstep;
;             const char* a2 = last ? nA : cA + (size_t)(t + 2) * kstep; const char* b2 = last ? nB : cB + (size_t)(t + 2) * kstep;
;             const char* a3 = a2 + kstep; const char* b3 = b2 + kstep;
;             if (last && has_next) S.a_ready(nxt);
;             if constexpr (SP2) {
;             PG8_LDB(B0, 0, 0); PG8_LDB(B1, 0, 1); PG8_SCHED; PG8_LDA(At, 0, 0); PG8_STAGE(PG8_SA(1, 1), a1 + hstep, voffA);
;             PG8_WAIT_V(8); PG8_WAIT_L(0); PG8_BAR; PG8_MMA(0, 0, At, B0); PG8_MMA(0, 1, At, B1); PG8_BAR; PG8_SCHED;
;             PG8_LDA(At, 0, 1); PG8_STAGE(PG8_SB(0, 0), b2, voffB); PG8_STAGE(PG8_SB(0, 1), b2 + hstep, voffB); PG8_STAGE(PG8_SA(0, 0), a2, voffA);
;             PG8_WAIT_V(8); PG8_WAIT_L(0); PG8_BAR; PG8_MMA(1, 0, At, B0); PG8_MMA(1, 1, At, B1); PG8_BAR; PG8_SCHED;
;             PG8_LDB(B0, 1, 0); PG8_LDB(B1, 1, 1); PG8_SCHED; PG8_LDA(At, 1, 0); PG8_STAGE(PG8_SA(0, 1), a2 + hstep, voffA);
;             PG8_WAIT_V(8); PG8_WAIT_L(0); PG8_BAR; PG8_MMA(0, 0, At, B0); PG8_MMA(0, 1, At, B1); PG8_BAR; PG8_SCHED;
;             PG8_LDA(At, 1, 1); PG8_STAGE(PG8_SB(1, 0), b3, voffB); PG8_STAGE(PG8_SB(1, 1), b3 + hstep, voffB); PG8_STAGE(PG8_SA(1, 0), a3, voffA);
;             PG8_WAIT_V(8); PG8_WAIT_L(0); PG8_BAR; PG8_MMA(1, 0, At, B0); PG8_MMA(1, 1, At, B1); PG8_BAR; PG8_SCHED;
.LBB0_1593:
	s_sub_i32 vcc_hi, 0x29000, s100
	s_sub_i32 vcc_hi, vcc_hi, s101
	s_add_u32 s40, s38, 0x100
	s_addc_u32 s41, s39, 0
	s_add_i32 s65, 0, 0x10000
	s_cmpk_eq_i32 s64, 0x54
	s_cselect_b32 s45, s7, s41
	s_cselect_b32 s44, s6, s40
	v_add_u32_e32 v144, s65, v147
	s_cselect_b32 s43, s27, s63
	s_cselect_b32 s42, s26, s62
	s_add_i32 s66, 0, 0x14000
	ds_read_b128 v[136:139], v144
	ds_read_b128 v[140:143], v144 offset:1024
	ds_read_b128 v[150:153], v144 offset:2048
	ds_read_b128 v[154:157], v144 offset:3072
	v_add_u32_e32 v144, s66, v147
	ds_read_b128 v[158:161], v144
	ds_read_b128 v[162:165], v144 offset:1024
	ds_read_b128 v[166:169], v144 offset:2048
	ds_read_b128 v[170:173], v144 offset:3072
	s_add_i32 m0, s47, 0xc000
	v_add_u32_e32 v250, s100, v149
	ds_read_b128 v[174:177], v250
	ds_read_b128 v[178:181], v250 offset:1024
	ds_read_b128 v[182:185], v250 offset:2048
	ds_read_b128 v[186:189], v250 offset:3072
	ds_read_b128 v[190:193], v250 offset:4096
	ds_read_b128 v[202:205], v250 offset:5120
	ds_read_b128 v[206:209], v250 offset:6144
	ds_read_b128 v[210:213], v250 offset:7168
	global_load_lds_dwordx4 v132, s[38:39]
	s_add_i32 m0, s47, 0xe000
	s_nop 0
	global_load_lds_dwordx4 v134, s[38:39]
	s_add_i32 m0, vcc_hi, s47
	s_nop 0
	global_load_lds_dwordx4 v0, s[44:45]
	s_add_i32 m0, m0, 0x2000
	s_nop 0
	global_load_lds_dwordx4 v130, s[44:45]
	s_waitcnt vmcnt(10)
	s_waitcnt lgkmcnt(0)
	s_setprio 1
	s_waitcnt lgkmcnt(0)
	v_mfma_f32_16x16x32_bf16 v[98:101], v[136:139], v[174:177], v[98:101]
	v_mfma_f32_16x16x32_bf16 v[34:37], v[150:153], v[174:177], v[34:37]
	v_mfma_f32_16x16x32_bf16 v[102:105], v[136:139], v[182:185], v[102:105]
	v_mfma_f32_16x16x32_bf16 v[42:45], v[150:153], v[182:185], v[42:45]
	s_barrier
	v_mfma_f32_16x16x32_bf16 v[106:109], v[136:139], v[190:193], v[106:109]
	v_mfma_f32_16x16x32_bf16 v[50:53], v[150:153], v[190:193], v[50:53]
	v_mfma_f32_16x16x32_bf16 v[110:113], v[136:139], v[206:209], v[110:113]
	v_mfma_f32_16x16x32_bf16 v[58:61], v[150:153], v[206:209], v[58:61]
	v_mfma_f32_16x16x32_bf16 v[98:101], v[140:143], v[178:181], v[98:101]
	v_mfma_f32_16x16x32_bf16 v[34:37], v[154:157], v[178:181], v[34:37]
	v_mfma_f32_16x16x32_bf16 v[102:105], v[140:143], v[186:189], v[102:105]
	v_mfma_f32_16x16x32_bf16 v[42:45], v[154:157], v[186:189], v[42:45]
	v_mfma_f32_16x16x32_bf16 v[106:109], v[140:143], v[202:205], v[106:109]
	v_mfma_f32_16x16x32_bf16 v[50:53], v[154:157], v[202:205], v[50:53]
	v_mfma_f32_16x16x32_bf16 v[110:113], v[140:143], v[210:213], v[110:113]
	v_mfma_f32_16x16x32_bf16 v[58:61], v[154:157], v[210:213], v[58:61]
	s_setprio 0
	s_setprio 1
	v_mfma_f32_16x16x32_bf16 v[38:41], v[158:161], v[174:177], v[38:41]
	v_mfma_f32_16x16x32_bf16 v[2:5], v[166:169], v[174:177], v[2:5]
	v_mfma_f32_16x16x32_bf16 v[46:49], v[158:161], v[182:185], v[46:49]
	v_mfma_f32_16x16x32_bf16 v[6:9], v[166:169], v[182:185], v[6:9]
	v_mfma_f32_16x16x32_bf16 v[54:57], v[158:161], v[190:193], v[54:57]
	v_mfma_f32_16x16x32_bf16 v[10:13], v[166:169], v[190:193], v[10:13]
	v_mfma_f32_16x16x32_bf16 v[62:65], v[158:161], v[206:209], v[62:65]
	v_mfma_f32_16x16x32_bf16 v[14:17], v[166:169], v[206:209], v[14:17]
	v_mfma_f32_16x16x32_bf16 v[38:41], v[162:165], v[178:181], v[38:41]
	v_mfma_f32_16x16x32_bf16 v[2:5], v[170:173], v[178:181], v[2:5]
	v_mfma_f32_16x16x32_bf16 v[46:49], v[162:165], v[186:189], v[46:49]
	v_mfma_f32_16x16x32_bf16 v[6:9], v[170:173], v[186:189], v[6:9]
	v_mfma_f32_16x16x32_bf16 v[54:57], v[162:165], v[202:205], v[54:57]
	v_mfma_f32_16x16x32_bf16 v[10:13], v[170:173], v[202:205], v[10:13]
	v_mfma_f32_16x16x32_bf16 v[62:65], v[162:165], v[210:213], v[62:65]
	v_mfma_f32_16x16x32_bf16 v[14:17], v[170:173], v[210:213], v[14:17]
	s_setprio 0
	s_barrier
	s_add_i32 s38, s65, s31
	s_mov_b32 m0, s38
	ds_read_b128 v[174:177], v149 offset:16384
	ds_read_b128 v[178:181], v149 offset:17408
	ds_read_b128 v[182:185], v149 offset:18432
	ds_read_b128 v[186:189], v149 offset:19456
	ds_read_b128 v[190:193], v149 offset:20480
	ds_read_b128 v[202:205], v149 offset:21504
	ds_read_b128 v[206:209], v149 offset:22528
	ds_read_b128 v[210:213], v149 offset:23552
	global_load_lds_dwordx4 v0, s[42:43]
	s_add_i32 m0, s38, 0x2000
	s_add_u32 s38, s42, 0x160000
	s_addc_u32 s39, s43, 0
	s_add_i32 s65, s66, s31
	global_load_lds_dwordx4 v130, s[42:43]
	s_mov_b32 m0, s65
	s_nop 0
	global_load_lds_dwordx4 v0, s[38:39]
	s_add_i32 m0, s65, 0x2000
	s_nop 0
	global_load_lds_dwordx4 v130, s[38:39]
	s_waitcnt vmcnt(8)
	s_waitcnt lgkmcnt(0)
	s_setprio 1
	s_waitcnt lgkmcnt(0)
	v_mfma_f32_16x16x32_bf16 v[114:117], v[136:139], v[174:177], v[114:117]
	v_mfma_f32_16x16x32_bf16 v[66:69], v[150:153], v[174:177], v[66:69]
	v_mfma_f32_16x16x32_bf16 v[118:121], v[136:139], v[182:185], v[118:121]
	v_mfma_f32_16x16x32_bf16 v[74:77], v[150:153], v[182:185], v[74:77]
	s_barrier
; #define PG8_STAGE(bufoff, gbase, voff) do { _Pragma("unroll") for (int _i = 0; _i < 2; ++_i) \
;         __builtin_amdgcn_global_load_lds((const unsigned*)((const char*)(gbase) + (voff)[_i]), (PG8_LAS unsigned*)(lds + (bufoff) + ldsw + _i * 8192), 16, 0, 0); } while (0)
; #define PG8_LDA(dst, b, h) do { _Pragma("unroll") for (int m = 0; m < 4; ++m) _Pragma("unroll") for (int k = 0; k < 2; ++k) dst[m][k] = *(const PG8_LAS bf16x8*)(lds + PG8_SA(b, h) + aoff + m * 2048 + k * 1024); } while (0)
; #define PG8_LDB(dst, b, h) do { _Pragma("unroll") for (int n = 0; n < 2; ++n) _Pragma("unroll") for (int k = 0; k < 2; ++k) dst[n][k] = *(const PG8_LAS bf16x8*)(lds + PG8_SB(b, h) + boff + n * 2048 + k * 1024); } while (0)
; template <class Epi, class Sched, bool ALIGN_EPI = false, bool SP2 = false>
; __device__ __forceinline__ void gemm_phase(PG8_LAS unsigned char* lds, const Gemm g, const Sched& S, const Epi& E) {
;     ...
;         for (int t = 0; t < nt; t += 2) {
;             const bool last = (t == nt - 2);
;             const char* a1 = cA + (size_t)(t + 1) * kstep;
;             const char* a2 = last ? nA : cA + (size_t)(t + 2) * kstep; const char* b2 = last ? nB : cB + (size_t)(t + 2) * kstep;
;             const char* a3 = a2 + kstep; const char* b3 = b2 + kstep;
;             if (last && has_next) S.a_ready(nxt);
;             if constexpr (SP2) {
;             PG8_LDB(B0, 0, 0); PG8_LDB(B1, 0, 1); PG8_SCHED; PG8_LDA(At, 0, 0); PG8_STAGE(PG8_SA(1, 1), a1 + hstep, voffA);
;             PG8_WAIT_V(8); PG8_WAIT_L(0); PG8_BAR; PG8_MMA(0, 0, At, B0); PG8_MMA(0, 1, At, B1); PG8_BAR; PG8_SCHED;
;             PG8_LDA(At, 0, 1); PG8_STAGE(PG8_SB(0, 0), b2, voffB); PG8_STAGE(PG8_SB(0, 1), b2 + hstep, voffB); PG8_STAGE(PG8_SA(0, 0), a2, voffA);
;             PG8_WAIT_V(8); PG8_WAIT_L(0); PG8_BAR; PG8_MMA(1, 0, At, B0); PG8_MMA(1, 1, At, B1); PG8_BAR; PG8_SCHED;
;             PG8_LDB(B0, 1, 0); PG8_LDB(B1, 1, 1); PG8_SCHED; PG8_LDA(At, 1, 0); PG8_STAGE(PG8_SA(0, 1), a2 + hstep, voffA);
;             PG8_WAIT_V(8); PG8_WAIT_L(0); PG8_BAR; PG8_MMA(0, 0, At, B0); PG8_MMA(0, 1, At, B1); PG8_BAR; PG8_SCHED;
;             PG8_LDA(At, 1, 1); PG8_STAGE(PG8_SB(1, 0), b3, voffB); PG8_STAGE(PG8_SB(1, 1), b3 + hstep, voffB); PG8_STAGE(PG8_SA(1, 0), a3, voffA);
;             PG8_WAIT_V(8); PG8_WAIT_L(0); PG8_BAR; PG8_MMA(1, 0, At, B0); PG8_MMA(1, 1, At, B1); PG8_BAR; PG8_SCHED;
	v_mfma_f32_16x16x32_bf16 v[122:125], v[136:139], v[190:193], v[122:125]
	v_mfma_f32_16x16x32_bf16 v[82:85], v[150:153], v[190:193], v[82:85]
	v_mfma_f32_16x16x32_bf16 v[126:129], v[136:139], v[206:209], v[126:129]
	v_mfma_f32_16x16x32_bf16 v[90:93], v[150:153], v[206:209], v[90:93]
	v_mfma_f32_16x16x32_bf16 v[114:117], v[140:143], v[178:181], v[114:117]
	v_mfma_f32_16x16x32_bf16 v[66:69], v[154:157], v[178:181], v[66:69]
	v_mfma_f32_16x16x32_bf16 v[118:121], v[140:143], v[186:189], v[118:121]
	v_mfma_f32_16x16x32_bf16 v[74:77], v[154:157], v[186:189], v[74:77]
	v_mfma_f32_16x16x32_bf16 v[122:125], v[140:143], v[202:205], v[122:125]
	v_mfma_f32_16x16x32_bf16 v[82:85], v[154:157], v[202:205], v[82:85]
	v_mfma_f32_16x16x32_bf16 v[126:129], v[140:143], v[210:213], v[126:129]
	v_mfma_f32_16x16x32_bf16 v[90:93], v[154:157], v[210:213], v[90:93]
	s_setprio 0
	s_setprio 1
	v_mfma_f32_16x16x32_bf16 v[70:73], v[158:161], v[174:177], v[70:73]
	v_mfma_f32_16x16x32_bf16 v[18:21], v[166:169], v[174:177], v[18:21]
	v_mfma_f32_16x16x32_bf16 v[78:81], v[158:161], v[182:185], v[78:81]
	v_mfma_f32_16x16x32_bf16 v[22:25], v[166:169], v[182:185], v[22:25]
	v_mfma_f32_16x16x32_bf16 v[86:89], v[158:161], v[190:193], v[86:89]
	v_mfma_f32_16x16x32_bf16 v[26:29], v[166:169], v[190:193], v[26:29]
	v_mfma_f32_16x16x32_bf16 v[94:97], v[158:161], v[206:209], v[94:97]
	v_mfma_f32_16x16x32_bf16 v[30:33], v[166:169], v[206:209], v[30:33]
	v_mfma_f32_16x16x32_bf16 v[70:73], v[162:165], v[178:181], v[70:73]
	v_mfma_f32_16x16x32_bf16 v[18:21], v[170:173], v[178:181], v[18:21]
	v_mfma_f32_16x16x32_bf16 v[78:81], v[162:165], v[186:189], v[78:81]
	v_mfma_f32_16x16x32_bf16 v[22:25], v[170:173], v[186:189], v[22:25]
	v_mfma_f32_16x16x32_bf16 v[86:89], v[162:165], v[202:205], v[86:89]
	v_mfma_f32_16x16x32_bf16 v[26:29], v[170:173], v[202:205], v[26:29]
	v_mfma_f32_16x16x32_bf16 v[94:97], v[162:165], v[210:213], v[94:97]
	v_mfma_f32_16x16x32_bf16 v[30:33], v[170:173], v[210:213], v[30:33]
	s_setprio 0
	s_barrier
	s_add_i32 s65, 0, 0x18000
	s_add_i32 s66, 0, 0x1c000
	v_add_u32_e32 v154, s65, v147
	v_add_u32_e32 v170, s66, v147
	ds_read_b128 v[136:139], v154
	ds_read_b128 v[140:143], v154 offset:1024
	ds_read_b128 v[150:153], v154 offset:2048
	ds_read_b128 v[154:157], v154 offset:3072
	ds_read_b128 v[158:161], v170
	ds_read_b128 v[162:165], v170 offset:1024
	ds_read_b128 v[166:169], v170 offset:2048
	ds_read_b128 v[170:173], v170 offset:3072
	s_add_u32 s38, s44, 0x160000
	s_addc_u32 s39, s45, 0
	s_mov_b32 m0, s49
	v_add_u32_e32 v250, s101, v149
	ds_read_b128 v[174:177], v250
	ds_read_b128 v[178:181], v250 offset:1024
	ds_read_b128 v[182:185], v250 offset:2048
	ds_read_b128 v[186:189], v250 offset:3072
	ds_read_b128 v[190:193], v250 offset:4096
	ds_read_b128 v[202:205], v250 offset:5120
	ds_read_b128 v[206:209], v250 offset:6144
	ds_read_b128 v[210:213], v250 offset:7168
	global_load_lds_dwordx4 v0, s[38:39]
	s_mov_b32 m0, s50
	s_nop 0
	global_load_lds_dwordx4 v130, s[38:39]
	s_add_i32 m0, s100, s47
	s_nop 0
	s_add_u32 s44, s44, 0x80
	s_addc_u32 s45, s45, 0
	global_load_lds_dwordx4 v0, s[44:45]
	s_add_i32 m0, m0, 0x2000
	s_nop 0
	global_load_lds_dwordx4 v130, s[44:45]
	s_waitcnt vmcnt(10)
	s_waitcnt lgkmcnt(0)
	s_setprio 1
	s_waitcnt lgkmcnt(0)
	v_mfma_f32_16x16x32_bf16 v[98:101], v[136:139], v[174:177], v[98:101]
	v_mfma_f32_16x16x32_bf16 v[34:37], v[150:153], v[174:177], v[34:37]
	v_mfma_f32_16x16x32_bf16 v[102:105], v[136:139], v[182:185], v[102:105]
	v_mfma_f32_16x16x32_bf16 v[42:45], v[150:153], v[182:185], v[42:45]
	s_barrier
; #define PG8_STAGE(bufoff, gbase, voff) do { _Pragma("unroll") for (int _i = 0; _i < 2; ++_i) \
;         __builtin_amdgcn_global_load_lds((const unsigned*)((const char*)(gbase) + (voff)[_i]), (PG8_LAS unsigned*)(lds + (bufoff) + ldsw + _i * 8192), 16, 0, 0); } while (0)
; #define PG8_LDA(dst, b, h) do { _Pragma("unroll") for (int m = 0; m < 4; ++m) _Pragma("unroll") for (int k = 0; k < 2; ++k) dst[m][k] = *(const PG8_LAS bf16x8*)(lds + PG8_SA(b, h) + aoff + m * 2048 + k * 1024); } while (0)
; #define PG8_LDB(dst, b, h) do { _Pragma("unroll") for (int n = 0; n < 2; ++n) _Pragma("unroll") for (int k = 0; k < 2; ++k) dst[n][k] = *(const PG8_LAS bf16x8*)(lds + PG8_SB(b, h) + boff + n * 2048 + k * 1024); } while (0)
; template <class Epi, class Sched, bool ALIGN_EPI = false, bool SP2 = false>
; __device__ __forceinline__ void gemm_phase(PG8_LAS unsigned char* lds, const Gemm g, const Sched& S, const Epi& E) {
;     ...
;         for (int t = 0; t < nt; t += 2) {
;             const bool last = (t == nt - 2);
;             const char* a1 = cA + (size_t)(t + 1) * kstep;
;             const char* a2 = last ? nA : cA + (size_t)(t + 2) * kstep; const char* b2 = last ? nB : cB + (size_t)(t + 2) * kstep;
;             const char* a3 = a2 + kstep; const char* b3 = b2 + kstep;
;             if (last && has_next) S.a_ready(nxt);
;             if constexpr (SP2) {
;             PG8_LDB(B0, 0, 0); PG8_LDB(B1, 0, 1); PG8_SCHED; PG8_LDA(At, 0, 0); PG8_STAGE(PG8_SA(1, 1), a1 + hstep, voffA);
;             PG8_WAIT_V(8); PG8_WAIT_L(0); PG8_BAR; PG8_MMA(0, 0, At, B0); PG8_MMA(0, 1, At, B1); PG8_BAR; PG8_SCHED;
;             PG8_LDA(At, 0, 1); PG8_STAGE(PG8_SB(0, 0), b2, voffB); PG8_STAGE(PG8_SB(0, 1), b2 + hstep, voffB); PG8_STAGE(PG8_SA(0, 0), a2, voffA);
;             PG8_WAIT_V(8); PG8_WAIT_L(0); PG8_BAR; PG8_MMA(1, 0, At, B0); PG8_MMA(1, 1, At, B1); PG8_BAR; PG8_SCHED;
;             PG8_LDB(B0, 1, 0); PG8_LDB(B1, 1, 1); PG8_SCHED; PG8_LDA(At, 1, 0); PG8_STAGE(PG8_SA(0, 1), a2 + hstep, voffA);
;             PG8_WAIT_V(8); PG8_WAIT_L(0); PG8_BAR; PG8_MMA(0, 0, At, B0); PG8_MMA(0, 1, At, B1); PG8_BAR; PG8_SCHED;
;             PG8_LDA(At, 1, 1); PG8_STAGE(PG8_SB(1, 0), b3, voffB); PG8_STAGE(PG8_SB(1, 1), b3 + hstep, voffB); PG8_STAGE(PG8_SA(1, 0), a3, voffA);
;             PG8_WAIT_V(8); PG8_WAIT_L(0); PG8_BAR; PG8_MMA(1, 0, At, B0); PG8_MMA(1, 1, At, B1); PG8_BAR; PG8_SCHED;
	v_mfma_f32_16x16x32_bf16 v[106:109], v[136:139], v[190:193], v[106:109]
	v_mfma_f32_16x16x32_bf16 v[50:53], v[150:153], v[190:193], v[50:53]
	v_mfma_f32_16x16x32_bf16 v[110:113], v[136:139], v[206:209], v[110:113]
	v_mfma_f32_16x16x32_bf16 v[58:61], v[150:153], v[206:209], v[58:61]
	v_mfma_f32_16x16x32_bf16 v[98:101], v[140:143], v[178:181], v[98:101]
	v_mfma_f32_16x16x32_bf16 v[34:37], v[154:157], v[178:181], v[34:37]
	v_mfma_f32_16x16x32_bf16 v[102:105], v[140:143], v[186:189], v[102:105]
	v_mfma_f32_16x16x32_bf16 v[42:45], v[154:157], v[186:189], v[42:45]
	v_mfma_f32_16x16x32_bf16 v[106:109], v[140:143], v[202:205], v[106:109]
	v_mfma_f32_16x16x32_bf16 v[50:53], v[154:157], v[202:205], v[50:53]
	v_mfma_f32_16x16x32_bf16 v[110:113], v[140:143], v[210:213], v[110:113]
	v_mfma_f32_16x16x32_bf16 v[58:61], v[154:157], v[210:213], v[58:61]
	s_setprio 0
	s_setprio 1
	v_mfma_f32_16x16x32_bf16 v[38:41], v[158:161], v[174:177], v[38:41]
	v_mfma_f32_16x16x32_bf16 v[2:5], v[166:169], v[174:177], v[2:5]
	v_mfma_f32_16x16x32_bf16 v[46:49], v[158:161], v[182:185], v[46:49]
	v_mfma_f32_16x16x32_bf16 v[6:9], v[166:169], v[182:185], v[6:9]
	v_mfma_f32_16x16x32_bf16 v[54:57], v[158:161], v[190:193], v[54:57]
	v_mfma_f32_16x16x32_bf16 v[10:13], v[166:169], v[190:193], v[10:13]
	v_mfma_f32_16x16x32_bf16 v[62:65], v[158:161], v[206:209], v[62:65]
	v_mfma_f32_16x16x32_bf16 v[14:17], v[166:169], v[206:209], v[14:17]
	v_mfma_f32_16x16x32_bf16 v[38:41], v[162:165], v[178:181], v[38:41]
	v_mfma_f32_16x16x32_bf16 v[2:5], v[170:173], v[178:181], v[2:5]
	v_mfma_f32_16x16x32_bf16 v[46:49], v[162:165], v[186:189], v[46:49]
	v_mfma_f32_16x16x32_bf16 v[6:9], v[170:173], v[186:189], v[6:9]
	v_mfma_f32_16x16x32_bf16 v[54:57], v[162:165], v[202:205], v[54:57]
	v_mfma_f32_16x16x32_bf16 v[10:13], v[170:173], v[202:205], v[10:13]
	v_mfma_f32_16x16x32_bf16 v[62:65], v[162:165], v[210:213], v[62:65]
	v_mfma_f32_16x16x32_bf16 v[14:17], v[170:173], v[210:213], v[14:17]
	s_setprio 0
	s_barrier
	s_add_i32 s38, s65, s31
	s_mov_b32 m0, s38
	ds_read_b128 v[174:177], v149 offset:49152
	ds_read_b128 v[178:181], v149 offset:50176
	ds_read_b128 v[182:185], v149 offset:51200
	ds_read_b128 v[186:189], v149 offset:52224
	ds_read_b128 v[190:193], v149 offset:53248
	ds_read_b128 v[202:205], v149 offset:54272
	ds_read_b128 v[206:209], v149 offset:55296
	ds_read_b128 v[210:213], v149 offset:56320
	s_add_u32 s42, s42, 0x80
	s_addc_u32 s43, s43, 0
	global_load_lds_dwordx4 v0, s[42:43]
	s_add_i32 m0, s38, 0x2000
	s_add_u32 s38, s42, 0x160000
	s_addc_u32 s39, s43, 0
	global_load_lds_dwordx4 v130, s[42:43]
	s_add_i32 s42, s66, s31
	s_mov_b32 m0, s42
	s_nop 0
	global_load_lds_dwordx4 v0, s[38:39]
	s_add_i32 m0, s42, 0x2000
	s_nop 0
	global_load_lds_dwordx4 v130, s[38:39]
	s_waitcnt vmcnt(8)
	s_waitcnt lgkmcnt(0)
	s_setprio 1
	s_waitcnt lgkmcnt(0)
	v_mfma_f32_16x16x32_bf16 v[114:117], v[136:139], v[174:177], v[114:117]
	v_mfma_f32_16x16x32_bf16 v[66:69], v[150:153], v[174:177], v[66:69]
	v_mfma_f32_16x16x32_bf16 v[118:121], v[136:139], v[182:185], v[118:121]
	v_mfma_f32_16x16x32_bf16 v[74:77], v[150:153], v[182:185], v[74:77]
	s_barrier
	v_mfma_f32_16x16x32_bf16 v[122:125], v[136:139], v[190:193], v[122:125]
	v_mfma_f32_16x16x32_bf16 v[82:85], v[150:153], v[190:193], v[82:85]
	v_mfma_f32_16x16x32_bf16 v[126:129], v[136:139], v[206:209], v[126:129]
	v_mfma_f32_16x16x32_bf16 v[90:93], v[150:153], v[206:209], v[90:93]
	v_mfma_f32_16x16x32_bf16 v[114:117], v[140:143], v[178:181], v[114:117]
	v_mfma_f32_16x16x32_bf16 v[66:69], v[154:157], v[178:181], v[66:69]
	v_mfma_f32_16x16x32_bf16 v[118:121], v[140:143], v[186:189], v[118:121]
	v_mfma_f32_16x16x32_bf16 v[74:77], v[154:157], v[186:189], v[74:77]
	v_mfma_f32_16x16x32_bf16 v[122:125], v[140:143], v[202:205], v[122:125]
	v_mfma_f32_16x16x32_bf16 v[82:85], v[154:157], v[202:205], v[82:85]
	v_mfma_f32_16x16x32_bf16 v[126:129], v[140:143], v[210:213], v[126:129]
	v_mfma_f32_16x16x32_bf16 v[90:93], v[154:157], v[210:213], v[90:93]
	s_setprio 0
	s_setprio 1
	v_mfma_f32_16x16x32_bf16 v[70:73], v[158:161], v[174:177], v[70:73]
	v_mfma_f32_16x16x32_bf16 v[18:21], v[166:169], v[174:177], v[18:21]
	v_mfma_f32_16x16x32_bf16 v[78:81], v[158:161], v[182:185], v[78:81]
	v_mfma_f32_16x16x32_bf16 v[22:25], v[166:169], v[182:185], v[22:25]
	v_mfma_f32_16x16x32_bf16 v[86:89], v[158:161], v[190:193], v[86:89]
	v_mfma_f32_16x16x32_bf16 v[26:29], v[166:169], v[190:193], v[26:29]
	v_mfma_f32_16x16x32_bf16 v[94:97], v[158:161], v[206:209], v[94:97]
	v_mfma_f32_16x16x32_bf16 v[30:33], v[166:169], v[206:209], v[30:33]
	v_mfma_f32_16x16x32_bf16 v[70:73], v[162:165], v[178:181], v[70:73]
	v_mfma_f32_16x16x32_bf16 v[18:21], v[170:173], v[178:181], v[18:21]
	v_mfma_f32_16x16x32_bf16 v[78:81], v[162:165], v[186:189], v[78:81]
	v_mfma_f32_16x16x32_bf16 v[22:25], v[170:173], v[186:189], v[22:25]
	v_mfma_f32_16x16x32_bf16 v[86:89], v[162:165], v[202:205], v[86:89]
	v_mfma_f32_16x16x32_bf16 v[26:29], v[170:173], v[202:205], v[26:29]
	v_mfma_f32_16x16x32_bf16 v[94:97], v[162:165], v[210:213], v[94:97]
	v_mfma_f32_16x16x32_bf16 v[30:33], v[170:173], v[210:213], v[30:33]
	s_setprio 0
	s_barrier
	s_add_i32 s64, s64, 2
	s_mov_b32 s101, s100
	s_mov_b32 s100, vcc_hi
	s_add_u32 s62, s62, 0x100
	s_addc_u32 s63, s63, 0
	s_cmpk_gt_u32 s64, 0x55
	s_mov_b64 s[38:39], s[40:41]
	s_cbranch_scc0 .LBB0_1593
	s_and_b64 vcc, exec, s[24:25]
	s_cbranch_vccz .LBB0_1596
	s_barrier
